# up GEMM tile order: 4 token panels x 8 column tiles per XCD round, panels 4..7 first and 0..3 last, so the U panels the down GEMM reads first are the most recently written (memory-side cache hits)
# baseline (speedup 1.0000x reference)
; #define PG8_STAGE(bufoff, gbase, voff) do { _Pragma("unroll") for (int _i = 0; _i < 2; ++_i) \
;         __builtin_amdgcn_global_load_lds((const unsigned*)((const char*)(gbase) + (voff)[_i]), (PG8_LAS unsigned*)(lds + (bufoff) + ldsw + _i * 8192), 16, 0, 0); } while (0)
; #define PG8_WAIT_V(n) asm volatile("s_waitcnt vmcnt(" #n ")" ::: "memory")
; #define PG8_BAR __builtin_amdgcn_s_barrier()
; template <class Epi, class Sched, bool ALIGN_EPI = false, bool SP2 = false>
; __device__ __forceinline__ void gemm_phase(PG8_LAS unsigned char* lds, const Gemm g, const Sched& S, const Epi& E) {
;     ...
;     const int tid = tid_, wid = __builtin_amdgcn_readfirstlane(tid >> 6), lane = tid & 63, wr = wid >> 2, wc = wid & 3, fr = lane & 15, fq = lane >> 4;
;     const int K = g.K, nt = K / BK;
;     unsigned voffA[2], voffB[2];
; #pragma unroll
;     for (int i = 0; i < 2; ++i) { int R, C; stage_rc(tid * 16 + i * 8192, R, C); const int Rb = Epi::PERM ? ((R & ~31) + perm32(R & 31)) : R;
;         voffA[i] = (unsigned)(R * K + C) * 2u; voffB[i] = (unsigned)(Rb * K + C) * 2u; }
;     const size_t kstep = (size_t)(BK * 2);
;     const size_t hstep = (size_t)HALF * K * 2;
;     const size_t tstep = 2 * hstep;
;     const unsigned ldsw = (unsigned)wid * 1024u;
;     const int aoff = lds_byte(wr * 64 + fr, fq * 8), boff = lds_byte(wc * 32 + fr, fq * 8);
;     ...
;     const char* cA = (const char*)g.A + (size_t)cur.pm * tstep; const char* cB = (const char*)g.Bt + (size_t)cur.pn * tstep;
;     S.a_ready(cur);
;     if constexpr (SP2) {
;         PG8_STAGE(PG8_SB(0, 0), cB, voffB); PG8_STAGE(PG8_SB(0, 1), cB + hstep, voffB); PG8_STAGE(PG8_SA(0, 0), cA, voffA); PG8_STAGE(PG8_SA(0, 1), cA + hstep, voffA);
;         if (wr == 1) PG8_BAR;
;         PG8_WAIT_V(2); PG8_BAR;
;         PG8_STAGE(PG8_SB(1, 0), cB + kstep, voffB); PG8_STAGE(PG8_SB(1, 1), cB + hstep + kstep, voffB);
;         PG8_WAIT_V(4); PG8_BAR;
.LBB0_590:
.LBB0_591:
	s_cmp_le_i32 s86, s20
	s_cselect_b64 s[46:47], -1, 0
	s_and_b64 s[4:5], s[46:47], s[4:5]
	s_andn2_b64 vcc, exec, s[4:5]
	s_cbranch_vccnz .LBB0_612
	v_readlane_b32 s6, v254, 52
	s_mov_b64 s[4:5], 0
	v_mov_b32_e32 v10, v230
	v_readlane_b32 s7, v254, 53
	s_andn2_b64 vcc, exec, s[6:7]
	v_readfirstlane_b32 s6, v10
	s_cbranch_vccnz .LBB0_612
	v_lshlrev_b32_e32 v0, 4, v10
	v_add_u32_e32 v1, 0x2000, v0
	v_ashrrev_i32_e32 v2, 31, v1
	v_lshrrev_b32_e32 v2, 22, v2
	v_add_u32_e32 v2, v1, v2
	v_ashrrev_i32_e32 v4, 10, v2
	v_mul_i32_i24_e32 v2, 0x400, v4
	v_sub_u32_e32 v1, v1, v2
	v_lshrrev_b32_e32 v2, 4, v1
	v_bitop3_b32 v1, v2, v1, 32 bitop3:0x6c
	v_ashrrev_i32_e32 v2, 31, v1
	v_lshrrev_b32_e32 v2, 26, v2
	v_add_u32_e32 v2, v1, v2
	s_waitcnt lgkmcnt(0)
	v_lshlrev_b32_e32 v3, 3, v4
	v_ashrrev_i32_e32 v5, 6, v2
	v_and_b32_e32 v3, -16, v3
	v_add_u32_e32 v3, v5, v3
	v_and_b32_e32 v6, 3, v5
	s_mov_b32 s8, 0xfffe0
	v_lshrrev_b32_e32 v7, 2, v3
	v_lshlrev_b32_e32 v8, 1, v3
	v_and_b32_e32 v2, 0xc0, v2
	v_and_or_b32 v6, v3, s8, v6
	v_and_b32_e32 v7, 4, v7
	v_and_b32_e32 v8, 24, v8
	v_sub_u32_e32 v1, v1, v2
	v_or3_b32 v7, v6, v7, v8
	v_lshlrev_b32_e32 v6, 5, v4
	v_ashrrev_i16_sdwa v1, v224, sext(v1) dst_sel:DWORD dst_unused:UNUSED_PAD src0_sel:DWORD src1_sel:BYTE_0
	v_and_b32_e32 v8, 32, v6
	v_bfe_i32 v6, v1, 0, 16
	v_add_lshl_u32 v1, v8, v6, 1
	v_lshl_add_u32 v128, v7, 12, v1
	v_lshl_add_u32 v130, v3, 12, v1
	v_bfe_i32 v1, v10, 27, 1
	v_lshrrev_b32_e32 v1, 22, v1
	v_add_u32_e32 v1, v0, v1
	v_and_b32_e32 v1, 0xfffffc00, v1
	v_sub_u32_e32 v0, v0, v1
	v_lshrrev_b32_e32 v1, 4, v0
	v_ashrrev_i32_e32 v2, 31, v10
	s_add_u32 s7, s50, s4
	v_bitop3_b32 v0, v1, v0, 32 bitop3:0x6c
	v_lshrrev_b32_e32 v2, 26, v2
	s_addc_u32 s16, s51, s5
	s_mul_i32 s4, s74, 0x6000000
	v_ashrrev_i32_e32 v1, 31, v0
	v_add_u32_e32 v2, v10, v2
	s_add_u32 s4, s7, s4
	v_lshrrev_b32_e32 v1, 26, v1
	v_ashrrev_i32_e32 v8, 6, v2
	s_addc_u32 s5, s16, 0
	v_add_u32_e32 v1, v0, v1
	v_lshlrev_b32_e32 v2, 3, v8
	s_add_u32 s20, s7, 0x39000000
	v_ashrrev_i32_e32 v7, 6, v1
	v_and_b32_e32 v2, -16, v2
	s_addc_u32 s21, s16, 0
	v_add_u32_e32 v2, v7, v2
	v_writelane_b32 v255, s0, 45
	s_add_u32 s22, s4, 0x3000000
	v_and_b32_e32 v3, 3, v7
	v_lshrrev_b32_e32 v9, 2, v2
	v_lshlrev_b32_e32 v11, 1, v2
	v_and_b32_e32 v1, 0xc0, v1
	v_writelane_b32 v255, s1, 46
	s_addc_u32 s23, s5, 0
	s_ashr_i32 s4, s6, 6
	v_and_or_b32 v3, v2, s8, v3
	v_and_b32_e32 v9, 4, v9
	v_and_b32_e32 v11, 24, v11
	v_sub_u32_e32 v0, v0, v1
	s_ashr_i32 s5, s6, 8
	s_lshl_b32 s36, s4, 10
	v_or3_b32 v3, v3, v9, v11
	v_lshlrev_b32_e32 v9, 5, v8
	v_ashrrev_i16_sdwa v0, v224, sext(v0) dst_sel:DWORD dst_unused:UNUSED_PAD src0_sel:DWORD src1_sel:BYTE_0
	v_readlane_b32 s8, v255, 12
	v_and_b32_e32 v11, 32, v9
	v_bfe_i32 v9, v0, 0, 16
	v_readlane_b32 s9, v255, 13
	v_readlane_b32 s32, v255, 16
	s_nop 3
	s_bfe_u32 s32, s32, 0x10002
	s_lshl_b32 s8, s8, 1
	s_lshl_b32 s33, s32, 20
	s_add_u32 s8, s8, s33
	s_ashr_i32 s33, s48, 31
	s_add_u32 s10, s22, s8
	v_add_lshl_u32 v0, v11, v9, 1
	s_addc_u32 s11, s23, s9
	s_add_i32 s37, s36, 0
	v_lshl_add_u32 v204, v3, 12, v0
	s_add_i32 m0, s37, 0x10000
	v_lshl_add_u32 v132, v2, 12, v0
	global_load_lds_dwordx4 v204, s[10:11]
	s_add_i32 m0, s37, 0x12000
	s_add_u32 s8, s10, 0x80000
	global_load_lds_dwordx4 v128, s[10:11]
	s_addc_u32 s9, s11, 0
	s_add_i32 m0, s37, 0x14000
	v_mov_b32_e32 v129, v205
	global_load_lds_dwordx4 v204, s[8:9]
	s_add_i32 m0, s37, 0x16000
	v_lshl_add_u64 v[0:1], s[10:11], 0, v[204:205]
	global_load_lds_dwordx4 v128, s[8:9]
	v_readlane_b32 s8, v255, 18
	v_readlane_b32 s9, v255, 19
	s_nop 3
	s_bitset1_b32 s8, 22
	s_add_u32 s8, s20, s8
	s_addc_u32 s9, s21, s9
	s_add_i32 s57, s37, 0x2000
	s_mov_b32 m0, s37
	s_add_u32 s34, s8, 0x80000
	global_load_lds_dwordx4 v132, s[8:9]
	s_mov_b32 m0, s57
	s_addc_u32 s35, s9, 0
	s_add_i32 s75, s37, 0x4000
	global_load_lds_dwordx4 v130, s[8:9]
	s_mov_b32 m0, s75
	s_add_i32 s84, s37, 0x6000
	global_load_lds_dwordx4 v132, s[34:35]
	s_mov_b32 m0, s84
	s_cmp_eq_u32 s5, 1
	global_load_lds_dwordx4 v130, s[34:35]
	s_cselect_b64 s[76:77], -1, 0
	s_cmp_lg_u32 s5, 1
	v_lshl_add_u64 v[2:3], s[10:11], 0, v[128:129]
	s_cbranch_scc1 .LBB0_595
	s_barrier
.LBB0_595:
	s_add_u32 s72, s7, 0x25000000
	s_addc_u32 s73, s16, 0
	s_add_u32 s88, s7, 0x300000
	v_lshrrev_b32_e32 v12, 1, v10
	s_addc_u32 s89, s16, 0
	v_and_b32_e32 v12, 24, v12
	s_lshl_b32 s4, s4, 5
	v_and_b32_e32 v11, 15, v10
	v_lshlrev_b32_e32 v13, 1, v12
	v_lshlrev_b32_e32 v10, 2, v10
	s_and_b32 s7, s4, 0x60
	s_add_i32 m0, s37, 0x18000
	v_lshl_add_u64 v[0:1], v[0:1], 0, s[26:27]
	v_lshl_or_b32 v142, s5, 6, v11
	v_lshl_or_b32 v11, v11, 6, v13
	s_lshl_b32 s5, s5, 13
	v_and_b32_e32 v10, 32, v10
	s_lshl_b32 s4, s7, 7
	s_waitcnt vmcnt(2)
	s_barrier
	global_load_lds_dwordx4 v[0:1], off
	s_add_i32 m0, s37, 0x1a000
	v_bitop3_b32 v143, v11, s4, v10 bitop3:0xde
	s_add_u32 s4, s10, 0x80080
	v_bitop3_b32 v13, v11, s5, v10 bitop3:0xde
	v_lshl_add_u64 v[0:1], v[2:3], 0, s[26:27]
	s_addc_u32 s5, s11, 0
	global_load_lds_dwordx4 v[0:1], off
	s_add_i32 m0, s37, 0x1c000
	v_lshl_add_u64 v[0:1], s[4:5], 0, v[204:205]
	global_load_lds_dwordx4 v[0:1], off
	v_lshl_add_u64 v[0:1], s[4:5], 0, v[128:129]
	s_add_i32 m0, s37, 0x1e000
	s_cmpk_lt_u32 s6, 0x100
	global_load_lds_dwordx4 v[0:1], off
	v_lshlrev_b32_e32 v0, 15, v4
	v_and_b32_e32 v0, 0xffff0000, v0
	v_lshl_add_u32 v0, v5, 12, v0
	v_and_b32_e32 v1, 1, v4
	v_lshl_or_b32 v0, v1, 6, v0
	v_lshl_add_u32 v134, v6, 1, v0
	v_lshlrev_b32_e32 v0, 15, v8
	v_and_b32_e32 v0, 0xffff0000, v0
	s_waitcnt vmcnt(4)
	v_lshl_add_u32 v0, v7, 12, v0
	v_and_b32_e32 v1, 1, v8
	v_or_b32_e32 v144, s7, v12
	v_lshl_or_b32 v0, v1, 6, v0
	v_readlane_b32 s6, v255, 16
	v_mov_b32_e32 v133, v205
	v_mov_b32_e32 v131, v205
	s_cselect_b64 s[4:5], -1, 0
	v_mov_b32_e32 v135, v205
	v_lshl_add_u32 v136, v9, 1, v0
	v_mov_b32_e32 v137, v205
	s_mov_b32 s97, 0
	v_add_u32_e32 v145, 0, v13
	v_readlane_b32 s34, v255, 11
	s_mov_b32 s35, s6
	s_bitset1_b32 s35, 2
	s_lshl_b32 s34, s34, 1
	s_add_i32 s34, s34, s32
	s_barrier
	v_readlane_b32 s7, v255, 17
	s_branch .LBB0_598

;     __host__ __device__ bool next(int i, Unit& u) const {
;         const long L = (long)i * G + c; if (L >= nwg) return false;
;         int wgid = (int)L; { const int q = nwg / NXCD, r = nwg % NXCD, xcd = wgid % NXCD, off = wgid / NXCD; wgid = (xcd < r ? xcd * (q + 1) : r * (q + 1) + (xcd - r) * q) + off; }
;         const int nig = WGM * nN, gid = wgid / nig, fm = gid * WGM, gsz = (nM - fm) < WGM ? (nM - fm) : WGM;
;         u.pm = fm + ((wgid % nig) % gsz); u.pn = (wgid % nig) / gsz; return true;
.LBB0_603:
	s_ashr_i32 s6, s17, 3
	s_add_i32 s6, s44, s6
	s_ashr_i32 s7, s6, 31
	s_lshr_b32 s7, s7, 24
	s_add_i32 s7, s6, s7
	s_ashr_i32 s16, s7, 8
	s_lshl_b32 s16, s16, 3
	s_sub_i32 s17, 64, s16
	s_min_i32 s17, s17, 8
	s_abs_i32 s38, s17
	v_cvt_f32_u32_e32 v0, s38
	s_sub_i32 s44, 0, s38
	s_and_b32 s7, s7, 0xffffff00
	s_sub_i32 s7, s6, s7
	v_rcp_iflag_f32_e32 v0, v0
	s_abs_i32 s6, s7
	s_xor_b32 s39, s7, s17
	s_ashr_i32 s39, s39, 31
	v_mul_f32_e32 v0, 0x4f7ffffe, v0
	v_cvt_u32_f32_e32 v0, v0
	s_nop 0
	v_readfirstlane_b32 s45, v0
	s_mul_i32 s44, s44, s45
	s_mul_hi_u32 s44, s45, s44
	s_add_i32 s45, s45, s44
	s_mul_hi_u32 s44, s6, s45
	s_mul_i32 s45, s44, s38
	s_sub_i32 s6, s6, s45
	s_add_i32 s52, s44, 1
	s_sub_i32 s45, s6, s38
	s_cmp_ge_u32 s6, s38
	s_cselect_b32 s44, s52, s44
	s_cselect_b32 s6, s45, s6
	s_add_i32 s45, s44, 1
	s_cmp_ge_u32 s6, s38
	s_cselect_b32 s6, s45, s44
	s_xor_b32 s6, s6, s39
	s_sub_i32 s6, s6, s39
	s_mul_i32 s17, s6, s17
	s_sub_i32 s7, s7, s17
	s_add_i32 s94, s16, s7
	s_and_b32 s16, s94, 7
	s_and_b32 s17, s94, -8
	s_lshr_b32 s7, s6, 4
	s_xor_b32 s7, s7, 1
	s_lshl_b32 s7, s7, 2
	s_add_i32 s17, s17, s7
	s_and_b32 s7, s16, 3
	s_add_i32 s94, s17, s7
	s_lshr_b32 s7, s6, 2
	s_and_b32 s7, s7, 3
	s_lshl_b32 s7, s7, 3
	s_and_b32 s17, s6, 3
	s_lshl_b32 s17, s17, 1
	s_add_i32 s7, s7, s17
	s_lshr_b32 s16, s16, 2
	s_add_i32 s6, s7, s16
